# attention: row max, alpha and exp2 of the new score tile interleaved into the P.V MFMA stream (V fragments in the K-ring registers, finer lgkmcnt waits); mask before P.V; one barrier per half-step
# speedup vs baseline: 1.0105x; 1.0105x over previous
.LBB0_390:
	s_and_b32 s5, s5, 0x3fffffc0
	s_lshl_b32 s5, s5, 2
	s_add_i32 s5, s5, 0
	s_add_i32 s7, s5, 0x14000
	s_ashr_i32 s5, s6, 31
	s_lshr_b32 s5, s5, 26
	s_add_i32 s5, s5, s6
	s_addk_i32 s5, 0xff
	v_lshlrev_b32_e32 v58, 3, v186
	v_and_b32_e32 v15, 0xc0, v15
	v_lshlrev_b32_e32 v59, 1, v186
	s_ashr_i32 s6, s5, 6
	v_and_or_b32 v15, v58, 24, v15
	v_and_b32_e32 v59, 32, v59
	v_and_b32_e32 v58, 0x100, v58
	s_cmp_lg_u32 0, -1
	v_or3_b32 v15, v15, v59, v58
	s_cselect_b32 s5, 0, 0
	v_add_u32_e32 v190, s5, v15
	v_max_f32_e32 v15, v19, v19
	v_max_f32_e32 v58, v18, v18
	v_max_f32_e32 v15, v58, v15
	v_max3_f32 v15, v15, v20, v21
	v_max3_f32 v15, v15, v22, v23
	v_max3_f32 v15, v15, v24, v25
	v_max3_f32 v15, v15, v26, v27
	v_max3_f32 v15, v15, v28, v29
	v_max3_f32 v15, v15, v30, v31
	v_max3_f32 v15, v15, v32, v33
	v_max3_f32 v15, v15, v34, v35
	v_max3_f32 v15, v15, v36, v37
	v_max3_f32 v15, v15, v38, v39
	v_max3_f32 v15, v15, v40, v41
	v_max3_f32 v15, v15, v42, v43
	v_max3_f32 v15, v15, v44, v45
	v_max3_f32 v15, v15, v46, v47
	v_max3_f32 v15, v15, v48, v49
	v_mov_b32_e32 v58, v15
	s_nop 1
	v_permlane32_swap_b32_e32 v15, v58
	v_max_f32_e32 v58, v58, v58
	v_max_f32_e32 v15, v15, v15
	v_max_f32_e32 v15, v15, v58
	v_add_f32_e32 v58, 0x7149f2ca, v15
	v_mul_f32_e32 v58, 0x3d93cd3a, v58
	v_max_f32_e32 v15, 0xf149f2ca, v15
	v_cmp_ge_f32_e32 vcc, s86, v58
	v_sub_f32_e32 v58, 0xf149f2ca, v15
	v_mul_f32_e32 v58, 0x3dd53b94, v58
	v_exp_f32_e32 v58, v58
	s_cmp_eq_u64 vcc, exec
	s_cselect_b64 vcc, -1, 0
	v_cndmask_b32_e32 v208, v15, v173, vcc
	v_cndmask_b32_e64 v191, v58, 1.0, vcc
	v_mul_f32_e32 v58, 0xbdd53b94, v208
	v_fmamk_f32 v15, v18, 0x3dd53b94, v58
	v_fmamk_f32 v18, v19, 0x3dd53b94, v58
	v_fmamk_f32 v19, v20, 0x3dd53b94, v58
	v_fmamk_f32 v20, v21, 0x3dd53b94, v58
	v_fmamk_f32 v21, v22, 0x3dd53b94, v58
	v_fmamk_f32 v22, v23, 0x3dd53b94, v58
	v_fmamk_f32 v23, v24, 0x3dd53b94, v58
	v_fmamk_f32 v24, v25, 0x3dd53b94, v58
	v_fmamk_f32 v25, v26, 0x3dd53b94, v58
	v_fmamk_f32 v26, v27, 0x3dd53b94, v58
	v_fmamk_f32 v27, v28, 0x3dd53b94, v58
	v_fmamk_f32 v28, v29, 0x3dd53b94, v58
	v_fmamk_f32 v29, v30, 0x3dd53b94, v58
	v_fmamk_f32 v30, v31, 0x3dd53b94, v58
	v_fmamk_f32 v31, v32, 0x3dd53b94, v58
	v_mov_b32_e32 v32, v58
	v_fmac_f32_e32 v32, 0x3dd53b94, v33
	v_exp_f32_e32 v224, v15
	v_exp_f32_e32 v226, v18
	v_exp_f32_e32 v222, v19
	v_exp_f32_e32 v225, v20
	v_exp_f32_e32 v220, v21
	v_exp_f32_e32 v223, v22
	v_exp_f32_e32 v219, v23
	v_exp_f32_e32 v221, v24
	v_exp_f32_e32 v216, v25
	v_exp_f32_e32 v218, v26
	v_exp_f32_e32 v214, v27
	v_exp_f32_e32 v217, v28
	v_exp_f32_e32 v212, v29
	v_exp_f32_e32 v215, v30
	v_exp_f32_e32 v211, v31
	v_exp_f32_e32 v213, v32
	s_waitcnt vmcnt(0)
	s_or_b32 s5, s4, 31
	v_pk_fma_f32 v[160:161], v[48:49], s[30:31], v[58:59] op_sel_hi:[1,0,0]
	v_pk_fma_f32 v[162:163], v[46:47], s[30:31], v[58:59] op_sel_hi:[1,0,0]
	v_pk_fma_f32 v[164:165], v[44:45], s[30:31], v[58:59] op_sel_hi:[1,0,0]
	v_pk_fma_f32 v[166:167], v[42:43], s[30:31], v[58:59] op_sel_hi:[1,0,0]
	v_pk_fma_f32 v[168:169], v[40:41], s[30:31], v[58:59] op_sel_hi:[1,0,0]
	v_pk_fma_f32 v[170:171], v[38:39], s[30:31], v[58:59] op_sel_hi:[1,0,0]
	v_pk_fma_f32 v[180:181], v[36:37], s[30:31], v[58:59] op_sel_hi:[1,0,0]
	v_pk_fma_f32 v[182:183], v[34:35], s[30:31], v[58:59] op_sel_hi:[1,0,0]
	v_add_u32_e32 v209, 0xe000, v202
	s_cmp_lt_i32 s8, 0
	v_add_u32_e32 v207, 0xe000, v196
	v_add_u32_e32 v205, 0xe000, v197
	v_add_u32_e32 v206, 0xe000, v199
	v_add_u32_e32 v204, 0xe000, v198
	v_cmp_gt_u32_e64 s[8:9], 32, v186
	v_lshl_add_u32 v192, v187, 2, s7
	v_lshl_add_u32 v189, v17, 2, s7
	s_waitcnt vmcnt(4)
	ds_write_b128 v200, v[6:9] offset:16384
	s_waitcnt vmcnt(2)
	ds_write_b128 v201, v[54:57] offset:16384
	ds_write_b128 v202, v[2:5] offset:57344
	s_waitcnt vmcnt(1)
	ds_write_b128 v209, v[10:13] offset:12288
	s_waitcnt vmcnt(0)
	ds_write_b128 v203, v[50:53] offset:57344
	s_waitcnt lgkmcnt(0)
	s_barrier
	s_cbranch_scc1 .LBB0_419
	v_mov_b32_e32 v15, v1
	s_add_i32 s7, s4, 0xbfffff45
	v_lshl_add_u64 v[176:177], s[48:49], 0, v[14:15]
	v_lshl_add_u64 v[178:179], s[50:51], 0, v[0:1]
	v_add_u32_e32 v0, s7, v187
	v_mov_b32_e32 v14, v1
	v_sub_u32_e32 v210, v0, v17
	v_mov_b32_e32 v0, v1
	v_mov_b32_e32 v2, v1
	v_mov_b32_e32 v3, v1
	v_mov_b32_e32 v4, v1
	v_mov_b32_e32 v5, v1
	v_mov_b32_e32 v6, v1
	v_mov_b32_e32 v7, v1
	v_mov_b32_e32 v8, v1
	v_mov_b32_e32 v9, v1
	v_mov_b32_e32 v10, v1
	v_mov_b32_e32 v11, v1
	v_mov_b32_e32 v12, v1
	v_mov_b32_e32 v13, v1
	v_mov_b64_e32 v[94:95], v[14:15]
	v_mov_b64_e32 v[78:79], v[14:15]
	v_mov_b64_e32 v[62:63], v[14:15]
	v_mov_b64_e32 v[46:47], v[14:15]
	v_mov_b32_e32 v194, 0
	s_mov_b32 s7, 1
	s_movk_i32 s54, 0x7f
	v_mov_b64_e32 v[92:93], v[12:13]
	v_mov_b64_e32 v[90:91], v[10:11]
	v_mov_b64_e32 v[88:89], v[8:9]
	v_mov_b64_e32 v[86:87], v[6:7]
	v_mov_b64_e32 v[84:85], v[4:5]
	v_mov_b64_e32 v[82:83], v[2:3]
	v_mov_b64_e32 v[80:81], v[0:1]
	v_mov_b64_e32 v[76:77], v[12:13]
	v_mov_b64_e32 v[74:75], v[10:11]
	v_mov_b64_e32 v[72:73], v[8:9]
	v_mov_b64_e32 v[70:71], v[6:7]
	v_mov_b64_e32 v[68:69], v[4:5]
	v_mov_b64_e32 v[66:67], v[2:3]
	v_mov_b64_e32 v[64:65], v[0:1]
	v_mov_b64_e32 v[60:61], v[12:13]
	v_mov_b64_e32 v[58:59], v[10:11]
	v_mov_b64_e32 v[56:57], v[8:9]
	v_mov_b64_e32 v[54:55], v[6:7]
	v_mov_b64_e32 v[52:53], v[4:5]
	v_mov_b64_e32 v[50:51], v[2:3]
	v_mov_b64_e32 v[48:49], v[0:1]
	v_mov_b64_e32 v[44:45], v[12:13]
	v_mov_b64_e32 v[42:43], v[10:11]
	v_mov_b64_e32 v[40:41], v[8:9]
	v_mov_b64_e32 v[38:39], v[6:7]
	v_mov_b64_e32 v[36:37], v[4:5]
	v_mov_b64_e32 v[34:35], v[2:3]
	v_mov_b64_e32 v[32:33], v[0:1]
	s_branch .LBB0_394
.LBB0_394:
	s_sub_i32 s10, s54, 63
	s_cmp_le_i32 s10, s5
	s_cselect_b64 s[76:77], -1, 0
	s_cmp_gt_i32 s10, s5
	s_cbranch_scc1 .LBB0_396
	ds_read_b128 v[236:239], v196 offset:57344
	ds_read_b128 v[240:243], v207 offset:12288
	ds_read_b128 v[246:249], v197 offset:57344
	ds_read_b128 v[250:253], v205 offset:12288
	ds_read_b128 v[6:9], v195
	ds_read_b128 v[10:13], v195 offset:1024
	ds_read_b128 v[2:5], v195 offset:2048
	v_cvt_pk_bf16_f32 v18, v224, v226
	v_cvt_pk_bf16_f32 v19, v222, v225
	v_cvt_pk_bf16_f32 v20, v220, v223
	v_cvt_pk_bf16_f32 v21, v219, v221
	v_cvt_pk_bf16_f32 v22, v216, v218
	v_cvt_pk_bf16_f32 v23, v214, v217
	v_cvt_pk_bf16_f32 v24, v212, v215
	v_cvt_pk_bf16_f32 v25, v211, v213
	v_add_f32_e32 v0, 0, v224
	v_add_f32_e32 v0, v226, v0
	v_add_f32_e32 v0, v222, v0
	v_add_f32_e32 v0, v225, v0
	v_add_f32_e32 v0, v220, v0
	v_add_f32_e32 v0, v223, v0
	v_add_f32_e32 v0, v219, v0
	v_add_f32_e32 v0, v221, v0
	s_waitcnt lgkmcnt(6)
	v_mfma_f32_32x32x16_bf16 v[112:127], v[236:239], v[156:159], 0
	ds_read_b128 v[236:239], v199 offset:57344
	v_add_f32_e32 v0, v216, v0
	v_add_f32_e32 v0, v218, v0
	v_permlane32_swap_b32_e32 v18, v20
	s_waitcnt lgkmcnt(6)
	v_mfma_f32_32x32x16_bf16 v[96:111], v[240:243], v[156:159], 0
	ds_read_b128 v[240:243], v206 offset:12288
	v_add_f32_e32 v0, v214, v0
	v_add_f32_e32 v0, v217, v0
	v_permlane32_swap_b32_e32 v19, v21
	s_waitcnt lgkmcnt(6)
	v_mfma_f32_32x32x16_bf16 v[112:127], v[246:249], v[152:155], v[112:127]
	ds_read_b128 v[246:249], v198 offset:57344
	v_add_f32_e32 v0, v212, v0
	v_add_f32_e32 v0, v215, v0
	s_waitcnt lgkmcnt(6)
	v_mfma_f32_32x32x16_bf16 v[96:111], v[250:253], v[152:155], v[96:111]
	ds_read_b128 v[250:253], v204 offset:12288
	v_permlane32_swap_b32_e32 v22, v24
	v_add_f32_e32 v0, v211, v0
	s_waitcnt lgkmcnt(3)
	v_mfma_f32_32x32x16_bf16 v[112:127], v[236:239], v[148:151], v[112:127]
	ds_read_b128 v[236:239], v196 offset:57472
	v_add_f32_e32 v0, v213, v0
	v_permlane32_swap_b32_e32 v23, v25
	s_waitcnt lgkmcnt(3)
	v_mfma_f32_32x32x16_bf16 v[96:111], v[240:243], v[148:151], v[96:111]
	ds_read_b128 v[240:243], v207 offset:12416
	v_exp_f32_e32 v182, v182
	v_exp_f32_e32 v183, v183
	s_waitcnt lgkmcnt(3)
	v_mfma_f32_32x32x16_bf16 v[112:127], v[246:249], v[144:147], v[112:127]
	ds_read_b128 v[246:249], v197 offset:57472
	v_exp_f32_e32 v180, v180
	v_exp_f32_e32 v181, v181
	s_waitcnt lgkmcnt(3)
	v_mfma_f32_32x32x16_bf16 v[96:111], v[250:253], v[144:147], v[96:111]
	ds_read_b128 v[250:253], v205 offset:12416
	v_add_f32_e32 v0, v182, v0
	v_exp_f32_e32 v170, v170
	s_waitcnt lgkmcnt(3)
	v_mfma_f32_32x32x16_bf16 v[112:127], v[236:239], v[140:143], v[112:127]
	ds_read_b128 v[236:239], v199 offset:57472
	v_add_f32_e32 v0, v183, v0
	v_exp_f32_e32 v171, v171
	s_waitcnt lgkmcnt(3)
	v_mfma_f32_32x32x16_bf16 v[96:111], v[240:243], v[140:143], v[96:111]
	ds_read_b128 v[240:243], v206 offset:12416
	v_add_f32_e32 v0, v180, v0
	v_exp_f32_e32 v168, v168
	s_waitcnt lgkmcnt(3)
	v_mfma_f32_32x32x16_bf16 v[112:127], v[246:249], v[136:139], v[112:127]
	ds_read_b128 v[246:249], v198 offset:57472
	v_add_f32_e32 v0, v181, v0
	v_exp_f32_e32 v169, v169
	s_waitcnt lgkmcnt(3)
	v_mfma_f32_32x32x16_bf16 v[96:111], v[250:253], v[136:139], v[96:111]
	ds_read_b128 v[250:253], v204 offset:12416
	v_cvt_pk_bf16_f32 v26, v182, v183
	v_cvt_pk_bf16_f32 v27, v180, v181
	s_waitcnt lgkmcnt(3)
	v_mfma_f32_32x32x16_bf16 v[112:127], v[236:239], v[132:135], v[112:127]
	ds_read_b128 v[236:239], v196 offset:57600
	v_add_f32_e32 v0, v170, v0
	v_exp_f32_e32 v166, v166
	s_waitcnt lgkmcnt(3)
	v_mfma_f32_32x32x16_bf16 v[96:111], v[240:243], v[132:135], v[96:111]
	ds_read_b128 v[240:243], v207 offset:12544
	v_add_f32_e32 v0, v171, v0
	v_exp_f32_e32 v167, v167
	s_waitcnt lgkmcnt(3)
	v_mfma_f32_32x32x16_bf16 v[112:127], v[246:249], v[128:131], v[112:127]
	ds_read_b128 v[246:249], v197 offset:57600
	v_add_f32_e32 v0, v168, v0
	v_exp_f32_e32 v164, v164
	s_waitcnt lgkmcnt(3)
	v_mfma_f32_32x32x16_bf16 v[96:111], v[250:253], v[128:131], v[96:111]
	ds_read_b128 v[250:253], v205 offset:12544
	v_add_f32_e32 v0, v169, v0
	v_exp_f32_e32 v165, v165
	s_waitcnt lgkmcnt(3)
	v_mfma_f32_32x32x16_bf16 v[112:127], v[236:239], v[6:9], v[112:127]
	ds_read_b128 v[236:239], v199 offset:57600
	v_cvt_pk_bf16_f32 v28, v170, v171
	v_cvt_pk_bf16_f32 v29, v168, v169
	s_waitcnt lgkmcnt(3)
	v_mfma_f32_32x32x16_bf16 v[96:111], v[240:243], v[6:9], v[96:111]
	ds_read_b128 v[240:243], v206 offset:12544
	ds_read_b128 v[6:9], v195 offset:3072
	v_add_f32_e32 v0, v166, v0
	v_exp_f32_e32 v162, v162
	s_waitcnt lgkmcnt(4)
	v_mfma_f32_32x32x16_bf16 v[112:127], v[246:249], v[10:13], v[112:127]
	ds_read_b128 v[246:249], v198 offset:57600
	v_permlane32_swap_b32_e32 v26, v28
	v_permlane32_swap_b32_e32 v27, v29
	s_waitcnt lgkmcnt(4)
	v_mfma_f32_32x32x16_bf16 v[96:111], v[250:253], v[10:13], v[96:111]
	ds_read_b128 v[250:253], v204 offset:12544
	v_add_f32_e32 v0, v167, v0
	v_exp_f32_e32 v163, v163
	s_waitcnt lgkmcnt(4)
	v_mfma_f32_32x32x16_bf16 v[112:127], v[236:239], v[2:5], v[112:127]
	v_add_f32_e32 v0, v164, v0
	v_exp_f32_e32 v160, v160
	s_waitcnt lgkmcnt(3)
	v_mfma_f32_32x32x16_bf16 v[96:111], v[240:243], v[2:5], v[96:111]
	v_add_f32_e32 v0, v165, v0
	v_exp_f32_e32 v161, v161
	s_waitcnt lgkmcnt(1)
	v_mfma_f32_32x32x16_bf16 v[112:127], v[246:249], v[6:9], v[112:127]
	v_cvt_pk_bf16_f32 v168, v166, v167
	v_cvt_pk_bf16_f32 v169, v164, v165
	s_waitcnt lgkmcnt(0)
	v_mfma_f32_32x32x16_bf16 v[96:111], v[250:253], v[6:9], v[96:111]
	v_add_f32_e32 v0, v162, v0
	v_add_f32_e32 v0, v163, v0
	v_add_f32_e32 v0, v160, v0
	v_add_f32_e32 v0, v161, v0
	v_cvt_pk_bf16_f32 v170, v162, v163
	v_cvt_pk_bf16_f32 v171, v160, v161
	v_mov_b32_e32 v14, v0
	s_nop 1
	v_permlane32_swap_b32_e32 v168, v170
	v_permlane32_swap_b32_e32 v169, v171
	v_permlane32_swap_b32_e32 v0, v14
	s_branch .Lattn_h1_join

.Lattn_h1_join:
	s_mov_b32 s10, 0xffe80000
	v_add_co_u32_e32 v6, vcc, s10, v178
	s_mov_b32 s10, 0xfff00000
	s_nop 0
	v_addc_co_u32_e32 v7, vcc, -1, v179, vcc
	v_add_co_u32_e32 v30, vcc, s10, v178
	s_nop 1
	v_addc_co_u32_e32 v31, vcc, -1, v179, vcc
	global_load_dwordx4 v[2:5], v[6:7], off
	s_nop 0
	global_load_dwordx4 v[6:9], v[6:7], off offset:-256
	s_nop 0
	global_load_dwordx4 v[10:13], v[30:31], off
	global_load_dwordx4 v[160:163], v[30:31], off offset:-256
	v_add_co_u32_e32 v30, vcc, 0xffffe000, v176
	s_nop 1
	v_addc_co_u32_e32 v31, vcc, -1, v177, vcc
	global_load_dwordx4 v[164:167], v[30:31], off
	s_nop 7
	s_nop 3
	s_cmp_le_i32 s54, s4
	s_cbranch_scc1 .Lh1_nomask
	v_add_u32_e32 v15, 0x4000007b, v210
	v_cmp_gt_u32_e32 vcc, 2.0, v15
	v_add_u32_e32 v15, 0x5b, v210
	s_nop 0
	v_cndmask_b32_e32 v112, v16, v112, vcc
	v_cmp_lt_u32_e32 vcc, s85, v15
	v_add_u32_e32 v15, 0x7a, v210
	s_nop 0
	v_cndmask_b32_e32 v96, v16, v96, vcc
	v_cmp_lt_u32_e32 vcc, s85, v15
	v_add_u32_e32 v15, 0x5a, v210
	s_nop 0
	v_cndmask_b32_e32 v113, v16, v113, vcc
	v_cmp_lt_u32_e32 vcc, s85, v15
	v_add_u32_e32 v15, 0x79, v210
	s_nop 0
	v_cndmask_b32_e32 v97, v16, v97, vcc
	v_cmp_lt_u32_e32 vcc, s85, v15
	v_add_u32_e32 v15, 0x59, v210
	s_nop 0
	v_cndmask_b32_e32 v114, v16, v114, vcc
	v_cmp_lt_u32_e32 vcc, s85, v15
	v_add_u32_e32 v15, 0x78, v210
	s_nop 0
	v_cndmask_b32_e32 v98, v16, v98, vcc
	v_cmp_lt_u32_e32 vcc, s85, v15
	v_add_u32_e32 v15, 0x58, v210
	s_nop 0
	v_cndmask_b32_e32 v115, v16, v115, vcc
	v_cmp_lt_u32_e32 vcc, s85, v15
	v_add_u32_e32 v15, 0x73, v210
	s_nop 0
	v_cndmask_b32_e32 v99, v16, v99, vcc
	v_cmp_lt_u32_e32 vcc, s85, v15
	v_add_u32_e32 v15, 0x53, v210
	s_nop 0
	v_cndmask_b32_e32 v116, v16, v116, vcc
	v_cmp_lt_u32_e32 vcc, s85, v15
	v_add_u32_e32 v15, 0x72, v210
	s_nop 0
	v_cndmask_b32_e32 v100, v16, v100, vcc
	v_cmp_lt_u32_e32 vcc, s85, v15
	v_add_u32_e32 v15, 0x52, v210
	s_nop 0
	v_cndmask_b32_e32 v117, v16, v117, vcc
	v_cmp_lt_u32_e32 vcc, s85, v15
	v_add_u32_e32 v15, 0x71, v210
	s_nop 0
	v_cndmask_b32_e32 v101, v16, v101, vcc
	v_cmp_lt_u32_e32 vcc, s85, v15
	v_add_u32_e32 v15, 0x51, v210
	s_nop 0
	v_cndmask_b32_e32 v118, v16, v118, vcc
	v_cmp_lt_u32_e32 vcc, s85, v15
	v_add_u32_e32 v15, 0x70, v210
	s_nop 0
	v_cndmask_b32_e32 v102, v16, v102, vcc
	v_cmp_lt_u32_e32 vcc, s85, v15
	v_add_u32_e32 v15, 0x50, v210
	s_nop 0
	v_cndmask_b32_e32 v119, v16, v119, vcc
	v_cmp_lt_u32_e32 vcc, s85, v15
	v_add_u32_e32 v15, 0x6b, v210
	s_nop 0
	v_cndmask_b32_e32 v103, v16, v103, vcc
	v_cmp_lt_u32_e32 vcc, s85, v15
	v_add_u32_e32 v15, 0x4b, v210
	s_nop 0
	v_cndmask_b32_e32 v120, v16, v120, vcc
	v_cmp_lt_u32_e32 vcc, s85, v15
	v_add_u32_e32 v15, 0x6a, v210
	s_nop 0
	v_cndmask_b32_e32 v104, v16, v104, vcc
	v_cmp_lt_u32_e32 vcc, s85, v15
	v_add_u32_e32 v15, 0x4a, v210
	s_nop 0
	v_cndmask_b32_e32 v121, v16, v121, vcc
	v_cmp_lt_u32_e32 vcc, s85, v15
	v_add_u32_e32 v15, 0x69, v210
	s_nop 0
	v_cndmask_b32_e32 v105, v16, v105, vcc
	v_cmp_lt_u32_e32 vcc, s85, v15
	v_add_u32_e32 v15, 0x49, v210
	s_nop 0
	v_cndmask_b32_e32 v122, v16, v122, vcc
	v_cmp_lt_u32_e32 vcc, s85, v15
	v_add_u32_e32 v15, 0x68, v210
	s_nop 0
	v_cndmask_b32_e32 v106, v16, v106, vcc
	v_cmp_lt_u32_e32 vcc, s85, v15
	v_add_u32_e32 v15, 0x48, v210
	s_nop 0
	v_cndmask_b32_e32 v123, v16, v123, vcc
	v_cmp_lt_u32_e32 vcc, s85, v15
	v_add_u32_e32 v15, 0x63, v210
	s_nop 0
	v_cndmask_b32_e32 v107, v16, v107, vcc
	v_cmp_lt_u32_e32 vcc, s85, v15
	v_add_u32_e32 v15, 0x43, v210
	s_nop 0
	v_cndmask_b32_e32 v124, v16, v124, vcc
	v_cmp_lt_u32_e32 vcc, s85, v15
	v_add_u32_e32 v15, 0x62, v210
	s_nop 0
	v_cndmask_b32_e32 v108, v16, v108, vcc
	v_cmp_lt_u32_e32 vcc, s85, v15
	v_add_u32_e32 v15, 0x42, v210
	s_nop 0
	v_cndmask_b32_e32 v125, v16, v125, vcc
	v_cmp_lt_u32_e32 vcc, s85, v15
	v_add_u32_e32 v15, 0x61, v210
	s_nop 0
	v_cndmask_b32_e32 v109, v16, v109, vcc
	v_cmp_lt_u32_e32 vcc, s85, v15
	v_add_u32_e32 v15, 0x41, v210
	s_nop 0
	v_cndmask_b32_e32 v126, v16, v126, vcc
	v_cmp_lt_u32_e32 vcc, s85, v15
	v_add_u32_e32 v15, 0x60, v210
	s_nop 0
	v_cndmask_b32_e32 v110, v16, v110, vcc
	v_cmp_lt_u32_e32 vcc, s85, v15
	v_add_u32_e32 v15, 64, v210
	s_nop 0
	v_cndmask_b32_e32 v127, v16, v127, vcc
	v_cmp_lt_u32_e32 vcc, s85, v15
	s_nop 1
	v_cndmask_b32_e32 v111, v16, v111, vcc
.Lh1_nomask:
	s_add_i32 s10, s54, 0xffffff81
	s_cmp_gt_i32 s10, s5
	s_cbranch_scc1 .Lh1_nopv
	ds_read_b64_tr_b16 v[236:237], v190 offset:0
	ds_read_b64_tr_b16 v[238:239], v190 offset:2048
	ds_read_b64_tr_b16 v[240:241], v190 offset:4096
	ds_read_b64_tr_b16 v[242:243], v190 offset:6144
	ds_read_b64_tr_b16 v[246:247], v190 offset:8192
	ds_read_b64_tr_b16 v[248:249], v190 offset:10240
	ds_read_b64_tr_b16 v[250:251], v190 offset:12288
	ds_read_b64_tr_b16 v[252:253], v190 offset:14336
	v_max_f32_e32 v15, v113, v113
	v_max_f32_e32 v17, v112, v112
	v_max_f32_e32 v15, v17, v15
	v_max3_f32 v15, v15, v114, v115
	v_max3_f32 v15, v15, v116, v117
	v_max3_f32 v15, v15, v118, v119
	v_max3_f32 v15, v15, v120, v121
	v_max3_f32 v15, v15, v122, v123
	v_max3_f32 v15, v15, v124, v125
	v_max3_f32 v15, v15, v126, v127
	v_max3_f32 v15, v15, v96, v97
	v_max3_f32 v15, v15, v98, v99
	v_max3_f32 v15, v15, v100, v101
	v_max3_f32 v15, v15, v102, v103
	v_max3_f32 v15, v15, v104, v105
	v_max3_f32 v15, v15, v106, v107
	v_max3_f32 v15, v15, v108, v109
	v_max3_f32 v15, v15, v110, v111
	s_waitcnt lgkmcnt(6)
	v_mfma_f32_32x32x16_bf16 v[80:95], v[18:21], v[236:239], v[80:95]
	ds_read_b64_tr_b16 v[236:237], v190 offset:512
	ds_read_b64_tr_b16 v[238:239], v190 offset:2560
	v_mov_b32_e32 v17, v15
	s_nop 1
	v_permlane32_swap_b32_e32 v15, v17
	v_max_f32_e32 v17, v17, v17
	s_waitcnt lgkmcnt(6)
	v_mfma_f32_32x32x16_bf16 v[80:95], v[22:25], v[240:243], v[80:95]
	ds_read_b64_tr_b16 v[240:241], v190 offset:4608
	ds_read_b64_tr_b16 v[242:243], v190 offset:6656
	v_max_f32_e32 v15, v15, v15
	v_max_f32_e32 v15, v15, v17
	v_sub_f32_e32 v17, v15, v208
	v_mul_f32_e32 v17, 0x3d93cd3a, v17
	s_waitcnt lgkmcnt(6)
	v_mfma_f32_32x32x16_bf16 v[80:95], v[26:29], v[246:249], v[80:95]
	ds_read_b64_tr_b16 v[246:247], v190 offset:8704
	ds_read_b64_tr_b16 v[248:249], v190 offset:10752
	v_cmp_ge_f32_e32 vcc, s86, v17
	v_max_f32_e32 v17, v208, v208
	v_max_f32_e32 v17, v17, v15
	v_sub_f32_e32 v15, v208, v17
	s_waitcnt lgkmcnt(6)
	v_mfma_f32_32x32x16_bf16 v[80:95], v[168:171], v[250:253], v[80:95]
	ds_read_b64_tr_b16 v[250:251], v190 offset:12800
	ds_read_b64_tr_b16 v[252:253], v190 offset:14848
	v_mul_f32_e32 v15, 0x3dd53b94, v15
	v_exp_f32_e32 v15, v15
	s_cmp_eq_u64 vcc, exec
	s_cselect_b64 s[10:11], -1, 0
	s_waitcnt lgkmcnt(6)
	v_mfma_f32_32x32x16_bf16 v[64:79], v[18:21], v[236:239], v[64:79]
	ds_read_b64_tr_b16 v[236:237], v190 offset:1024
	ds_read_b64_tr_b16 v[238:239], v190 offset:3072
	v_cndmask_b32_e64 v180, v17, v208, s[10:11]
	v_cndmask_b32_e64 v15, v15, 1.0, s[10:11]
	v_mul_f32_e32 v219, 0xbdd53b94, v180
	v_fmamk_f32 v216, v112, 0x3dd53b94, v219
	s_waitcnt lgkmcnt(6)
	v_mfma_f32_32x32x16_bf16 v[64:79], v[22:25], v[240:243], v[64:79]
	ds_read_b64_tr_b16 v[240:241], v190 offset:5120
	ds_read_b64_tr_b16 v[242:243], v190 offset:7168
	v_fmamk_f32 v218, v113, 0x3dd53b94, v219
	v_fmamk_f32 v214, v114, 0x3dd53b94, v219
	v_fmamk_f32 v217, v115, 0x3dd53b94, v219
	v_fmamk_f32 v212, v116, 0x3dd53b94, v219
	s_waitcnt lgkmcnt(6)
	v_mfma_f32_32x32x16_bf16 v[64:79], v[26:29], v[246:249], v[64:79]
	ds_read_b64_tr_b16 v[246:247], v190 offset:9216
	ds_read_b64_tr_b16 v[248:249], v190 offset:11264
	v_fmamk_f32 v215, v117, 0x3dd53b94, v219
	v_fmamk_f32 v211, v118, 0x3dd53b94, v219
	v_fmamk_f32 v213, v119, 0x3dd53b94, v219
	v_fmamk_f32 v182, v120, 0x3dd53b94, v219
	s_waitcnt lgkmcnt(6)
	v_mfma_f32_32x32x16_bf16 v[64:79], v[168:171], v[250:253], v[64:79]
	ds_read_b64_tr_b16 v[250:251], v190 offset:13312
	ds_read_b64_tr_b16 v[252:253], v190 offset:15360
	v_fmamk_f32 v208, v121, 0x3dd53b94, v219
	v_fmamk_f32 v183, v123, 0x3dd53b94, v219
	v_fmamk_f32 v181, v125, 0x3dd53b94, v219
	v_exp_f32_e32 v216, v216
	s_waitcnt lgkmcnt(6)
	v_mfma_f32_32x32x16_bf16 v[48:63], v[18:21], v[236:239], v[48:63]
	ds_read_b64_tr_b16 v[236:237], v190 offset:1536
	ds_read_b64_tr_b16 v[238:239], v190 offset:3584
	v_fmamk_f32 v220, v96, 0x3dd53b94, v219
	v_exp_f32_e32 v218, v218
	v_fmamk_f32 v221, v97, 0x3dd53b94, v219
	v_exp_f32_e32 v214, v214
	s_waitcnt lgkmcnt(6)
	v_mfma_f32_32x32x16_bf16 v[48:63], v[22:25], v[240:243], v[48:63]
	ds_read_b64_tr_b16 v[240:241], v190 offset:5632
	ds_read_b64_tr_b16 v[242:243], v190 offset:7680
	v_fmamk_f32 v222, v98, 0x3dd53b94, v219
	v_exp_f32_e32 v217, v217
	v_fmamk_f32 v223, v99, 0x3dd53b94, v219
	v_exp_f32_e32 v212, v212
	s_waitcnt lgkmcnt(6)
	v_mfma_f32_32x32x16_bf16 v[48:63], v[26:29], v[246:249], v[48:63]
	ds_read_b64_tr_b16 v[246:247], v190 offset:9728
	ds_read_b64_tr_b16 v[248:249], v190 offset:11776
	v_fmamk_f32 v224, v100, 0x3dd53b94, v219
	v_exp_f32_e32 v215, v215
	v_fmamk_f32 v225, v101, 0x3dd53b94, v219
	s_waitcnt lgkmcnt(6)
	v_mfma_f32_32x32x16_bf16 v[48:63], v[168:171], v[250:253], v[48:63]
	ds_read_b64_tr_b16 v[250:251], v190 offset:13824
	ds_read_b64_tr_b16 v[252:253], v190 offset:15872
	v_exp_f32_e32 v211, v211
	v_fmamk_f32 v226, v102, 0x3dd53b94, v219
	v_exp_f32_e32 v213, v213
	s_waitcnt lgkmcnt(6)
	v_mfma_f32_32x32x16_bf16 v[32:47], v[18:21], v[236:239], v[32:47]
	v_fmamk_f32 v227, v103, 0x3dd53b94, v219
	v_exp_f32_e32 v182, v182
	v_fmamk_f32 v228, v104, 0x3dd53b94, v219
	s_waitcnt lgkmcnt(4)
	v_mfma_f32_32x32x16_bf16 v[32:47], v[22:25], v[240:243], v[32:47]
	v_exp_f32_e32 v208, v208
	v_fmamk_f32 v229, v105, 0x3dd53b94, v219
	v_exp_f32_e32 v183, v183
	s_waitcnt lgkmcnt(2)
	v_mfma_f32_32x32x16_bf16 v[32:47], v[26:29], v[246:249], v[32:47]
	v_fmamk_f32 v230, v106, 0x3dd53b94, v219
	v_exp_f32_e32 v181, v181
	v_fmamk_f32 v231, v107, 0x3dd53b94, v219
	s_waitcnt lgkmcnt(0)
	v_mfma_f32_32x32x16_bf16 v[32:47], v[168:171], v[250:253], v[32:47]
	v_fmamk_f32 v232, v108, 0x3dd53b94, v219
	v_fmamk_f32 v233, v109, 0x3dd53b94, v219
	v_fmamk_f32 v234, v110, 0x3dd53b94, v219
	s_branch .Lh1_post
.Lh1_nopv:
	v_max_f32_e32 v15, v113, v113
	v_max_f32_e32 v17, v112, v112
	v_max_f32_e32 v15, v17, v15
	v_max3_f32 v15, v15, v114, v115
	v_max3_f32 v15, v15, v116, v117
	v_max3_f32 v15, v15, v118, v119
	v_max3_f32 v15, v15, v120, v121
	v_max3_f32 v15, v15, v122, v123
	v_max3_f32 v15, v15, v124, v125
	v_max3_f32 v15, v15, v126, v127
	v_max3_f32 v15, v15, v96, v97
	v_max3_f32 v15, v15, v98, v99
	v_max3_f32 v15, v15, v100, v101
	v_max3_f32 v15, v15, v102, v103
	v_max3_f32 v15, v15, v104, v105
	v_max3_f32 v15, v15, v106, v107
	v_max3_f32 v15, v15, v108, v109
	v_max3_f32 v15, v15, v110, v111
	v_mov_b32_e32 v17, v15
	s_nop 1
	v_permlane32_swap_b32_e32 v15, v17
	v_max_f32_e32 v17, v17, v17
	v_max_f32_e32 v15, v15, v15
	v_max_f32_e32 v15, v15, v17
	v_sub_f32_e32 v17, v15, v208
	v_mul_f32_e32 v17, 0x3d93cd3a, v17
	v_cmp_ge_f32_e32 vcc, s86, v17
	v_max_f32_e32 v17, v208, v208
	v_max_f32_e32 v17, v17, v15
	v_sub_f32_e32 v15, v208, v17
	v_mul_f32_e32 v15, 0x3dd53b94, v15
	v_exp_f32_e32 v15, v15
	s_cmp_eq_u64 vcc, exec
	s_cselect_b64 s[10:11], -1, 0
	v_cndmask_b32_e64 v180, v17, v208, s[10:11]
	v_cndmask_b32_e64 v15, v15, 1.0, s[10:11]
	v_mul_f32_e32 v219, 0xbdd53b94, v180
	v_fmamk_f32 v216, v112, 0x3dd53b94, v219
	v_fmamk_f32 v218, v113, 0x3dd53b94, v219
	v_fmamk_f32 v214, v114, 0x3dd53b94, v219
	v_fmamk_f32 v217, v115, 0x3dd53b94, v219
	v_fmamk_f32 v212, v116, 0x3dd53b94, v219
	v_fmamk_f32 v215, v117, 0x3dd53b94, v219
	v_fmamk_f32 v211, v118, 0x3dd53b94, v219
	v_fmamk_f32 v213, v119, 0x3dd53b94, v219
	v_fmamk_f32 v182, v120, 0x3dd53b94, v219
	v_fmamk_f32 v208, v121, 0x3dd53b94, v219
	v_fmamk_f32 v183, v123, 0x3dd53b94, v219
	v_fmamk_f32 v181, v125, 0x3dd53b94, v219
	v_exp_f32_e32 v216, v216
	v_fmamk_f32 v220, v96, 0x3dd53b94, v219
	v_exp_f32_e32 v218, v218
	v_fmamk_f32 v221, v97, 0x3dd53b94, v219
	v_exp_f32_e32 v214, v214
	v_fmamk_f32 v222, v98, 0x3dd53b94, v219
	v_exp_f32_e32 v217, v217
	v_fmamk_f32 v223, v99, 0x3dd53b94, v219
	v_exp_f32_e32 v212, v212
	v_fmamk_f32 v224, v100, 0x3dd53b94, v219
	v_exp_f32_e32 v215, v215
	v_fmamk_f32 v225, v101, 0x3dd53b94, v219
	v_exp_f32_e32 v211, v211
	v_fmamk_f32 v226, v102, 0x3dd53b94, v219
	v_exp_f32_e32 v213, v213
	v_fmamk_f32 v227, v103, 0x3dd53b94, v219
	v_exp_f32_e32 v182, v182
	v_fmamk_f32 v228, v104, 0x3dd53b94, v219
	v_exp_f32_e32 v208, v208
	v_fmamk_f32 v229, v105, 0x3dd53b94, v219
	v_exp_f32_e32 v183, v183
	v_fmamk_f32 v230, v106, 0x3dd53b94, v219
	v_exp_f32_e32 v181, v181
	v_fmamk_f32 v231, v107, 0x3dd53b94, v219
	v_fmamk_f32 v232, v108, 0x3dd53b94, v219
	v_fmamk_f32 v233, v109, 0x3dd53b94, v219
	v_fmamk_f32 v234, v110, 0x3dd53b94, v219
.Lh1_post:
	s_waitcnt vmcnt(0)
	ds_write_b128 v202, v[6:9] offset:32768
	ds_write_b128 v202, v[160:163] offset:45056
	ds_write_b128 v203, v[164:167] offset:32768
	v_cmp_gt_f32_e32 vcc, 1.0, v15
	s_cbranch_vccz .Lh1_norsc
	s_and_saveexec_b64 s[78:79], s[8:9]
	ds_write_b32 v192, v15 offset:128
	s_or_b64 exec, exec, s[78:79]
	s_waitcnt lgkmcnt(0)
	ds_read_b128 v[18:21], v189 offset:224
	ds_read_b128 v[22:25], v189 offset:192
	ds_read_b128 v[26:29], v189 offset:160
	ds_read_b128 v[168:171], v189 offset:128
	s_waitcnt lgkmcnt(3)
	v_pk_mul_f32 v[94:95], v[94:95], v[20:21]
	s_waitcnt lgkmcnt(2)
	v_pk_mul_f32 v[90:91], v[90:91], v[24:25]
	s_waitcnt lgkmcnt(1)
	v_pk_mul_f32 v[86:87], v[86:87], v[28:29]
	s_waitcnt lgkmcnt(0)
	v_pk_mul_f32 v[82:83], v[82:83], v[170:171]
	v_pk_mul_f32 v[92:93], v[92:93], v[18:19]
	v_pk_mul_f32 v[88:89], v[88:89], v[22:23]
	v_pk_mul_f32 v[84:85], v[84:85], v[26:27]
	v_pk_mul_f32 v[80:81], v[80:81], v[168:169]
	v_pk_mul_f32 v[78:79], v[78:79], v[20:21]
	v_pk_mul_f32 v[74:75], v[74:75], v[24:25]
	v_pk_mul_f32 v[70:71], v[70:71], v[28:29]
	v_pk_mul_f32 v[66:67], v[66:67], v[170:171]
	v_pk_mul_f32 v[76:77], v[76:77], v[18:19]
	v_pk_mul_f32 v[72:73], v[72:73], v[22:23]
	v_pk_mul_f32 v[68:69], v[68:69], v[26:27]
	v_pk_mul_f32 v[64:65], v[64:65], v[168:169]
	v_pk_mul_f32 v[62:63], v[62:63], v[20:21]
	v_pk_mul_f32 v[58:59], v[58:59], v[24:25]
	v_pk_mul_f32 v[54:55], v[54:55], v[28:29]
	v_pk_mul_f32 v[50:51], v[50:51], v[170:171]
	v_pk_mul_f32 v[60:61], v[60:61], v[18:19]
	v_pk_mul_f32 v[56:57], v[56:57], v[22:23]
	v_pk_mul_f32 v[52:53], v[52:53], v[26:27]
	v_pk_mul_f32 v[48:49], v[48:49], v[168:169]
	v_pk_mul_f32 v[46:47], v[46:47], v[20:21]
	v_pk_mul_f32 v[42:43], v[42:43], v[24:25]
	v_pk_mul_f32 v[38:39], v[38:39], v[28:29]
	v_pk_mul_f32 v[34:35], v[34:35], v[170:171]
	v_pk_mul_f32 v[44:45], v[44:45], v[18:19]
	v_pk_mul_f32 v[40:41], v[40:41], v[22:23]
	v_pk_mul_f32 v[36:37], v[36:37], v[26:27]
	v_pk_mul_f32 v[32:33], v[32:33], v[168:169]
.Lh1_norsc:
	v_fmamk_f32 v171, v122, 0x3dd53b94, v219
	v_fmamk_f32 v169, v124, 0x3dd53b94, v219
	v_fmamk_f32 v168, v126, 0x3dd53b94, v219
	v_fmamk_f32 v170, v127, 0x3dd53b94, v219
	v_exp_f32_e32 v171, v171
	v_exp_f32_e32 v169, v169
	v_exp_f32_e32 v168, v168
	v_exp_f32_e32 v170, v170
	v_fmac_f32_e32 v219, 0x3dd53b94, v111
	s_add_i32 s10, s54, 1
	s_waitcnt lgkmcnt(0)
	s_barrier
	ds_write_b128 v200, v[2:5]
	ds_write_b128 v201, v[10:13]
	s_cmp_gt_i32 s10, s5
	s_cbranch_scc1 .LBB0_407
	ds_read_b128 v[236:239], v196 offset:32768
	ds_read_b128 v[240:243], v196 offset:45056
	ds_read_b128 v[246:249], v197 offset:32768
	ds_read_b128 v[250:253], v197 offset:45056
	ds_read_b128 v[6:9], v195
	ds_read_b128 v[10:13], v195 offset:1024
	ds_read_b128 v[2:5], v195 offset:2048
	v_cvt_pk_bf16_f32 v18, v216, v218
	v_cvt_pk_bf16_f32 v19, v214, v217
	v_cvt_pk_bf16_f32 v20, v212, v215
	v_cvt_pk_bf16_f32 v21, v211, v213
	v_cvt_pk_bf16_f32 v22, v182, v208
	v_cvt_pk_bf16_f32 v23, v171, v183
	v_cvt_pk_bf16_f32 v24, v169, v181
	v_cvt_pk_bf16_f32 v25, v168, v170
	v_add_f32_e32 v17, 0, v216
	v_add_f32_e32 v17, v218, v17
	v_add_f32_e32 v17, v214, v17
	v_add_f32_e32 v17, v217, v17
	v_add_f32_e32 v17, v212, v17
	v_add_f32_e32 v17, v215, v17
	v_add_f32_e32 v17, v211, v17
	v_add_f32_e32 v17, v213, v17
	s_waitcnt lgkmcnt(6)
	v_mfma_f32_32x32x16_bf16 v[112:127], v[236:239], v[156:159], 0
	ds_read_b128 v[236:239], v199 offset:32768
	v_add_f32_e32 v17, v182, v17
	v_add_f32_e32 v17, v208, v17
	v_permlane32_swap_b32_e32 v18, v20
	s_waitcnt lgkmcnt(6)
	v_mfma_f32_32x32x16_bf16 v[96:111], v[240:243], v[156:159], 0
	ds_read_b128 v[240:243], v199 offset:45056
	v_add_f32_e32 v17, v171, v17
	v_add_f32_e32 v17, v183, v17
	v_permlane32_swap_b32_e32 v19, v21
	s_waitcnt lgkmcnt(6)
	v_mfma_f32_32x32x16_bf16 v[112:127], v[246:249], v[152:155], v[112:127]
	ds_read_b128 v[246:249], v198 offset:32768
	v_add_f32_e32 v17, v169, v17
	v_add_f32_e32 v17, v181, v17
	s_waitcnt lgkmcnt(6)
	v_mfma_f32_32x32x16_bf16 v[96:111], v[250:253], v[152:155], v[96:111]
	ds_read_b128 v[250:253], v198 offset:45056
	v_permlane32_swap_b32_e32 v22, v24
	v_add_f32_e32 v17, v168, v17
	s_waitcnt lgkmcnt(3)
	v_mfma_f32_32x32x16_bf16 v[112:127], v[236:239], v[148:151], v[112:127]
	ds_read_b128 v[236:239], v196 offset:32896
	v_add_f32_e32 v17, v170, v17
	v_permlane32_swap_b32_e32 v23, v25
	s_waitcnt lgkmcnt(3)
	v_mfma_f32_32x32x16_bf16 v[96:111], v[240:243], v[148:151], v[96:111]
	ds_read_b128 v[240:243], v196 offset:45184
	v_exp_f32_e32 v220, v220
	v_exp_f32_e32 v221, v221
	s_waitcnt lgkmcnt(3)
	v_mfma_f32_32x32x16_bf16 v[112:127], v[246:249], v[144:147], v[112:127]
	ds_read_b128 v[246:249], v197 offset:32896
	v_exp_f32_e32 v222, v222
	v_exp_f32_e32 v223, v223
	s_waitcnt lgkmcnt(3)
	v_mfma_f32_32x32x16_bf16 v[96:111], v[250:253], v[144:147], v[96:111]
	ds_read_b128 v[250:253], v197 offset:45184
	v_add_f32_e32 v17, v220, v17
	v_exp_f32_e32 v224, v224
	s_waitcnt lgkmcnt(3)
	v_mfma_f32_32x32x16_bf16 v[112:127], v[236:239], v[140:143], v[112:127]
	ds_read_b128 v[236:239], v199 offset:32896
	v_add_f32_e32 v17, v221, v17
	v_exp_f32_e32 v225, v225
	s_waitcnt lgkmcnt(3)
	v_mfma_f32_32x32x16_bf16 v[96:111], v[240:243], v[140:143], v[96:111]
	ds_read_b128 v[240:243], v199 offset:45184
	v_add_f32_e32 v17, v222, v17
	v_exp_f32_e32 v226, v226
	s_waitcnt lgkmcnt(3)
	v_mfma_f32_32x32x16_bf16 v[112:127], v[246:249], v[136:139], v[112:127]
	ds_read_b128 v[246:249], v198 offset:32896
	v_add_f32_e32 v17, v223, v17
	v_exp_f32_e32 v227, v227
	s_waitcnt lgkmcnt(3)
	v_mfma_f32_32x32x16_bf16 v[96:111], v[250:253], v[136:139], v[96:111]
	ds_read_b128 v[250:253], v198 offset:45184
	v_cvt_pk_bf16_f32 v26, v220, v221
	v_cvt_pk_bf16_f32 v27, v222, v223
	s_waitcnt lgkmcnt(3)
	v_mfma_f32_32x32x16_bf16 v[112:127], v[236:239], v[132:135], v[112:127]
	ds_read_b128 v[236:239], v196 offset:33024
	v_add_f32_e32 v17, v224, v17
	v_exp_f32_e32 v228, v228
	s_waitcnt lgkmcnt(3)
	v_mfma_f32_32x32x16_bf16 v[96:111], v[240:243], v[132:135], v[96:111]
	ds_read_b128 v[240:243], v196 offset:45312
	v_add_f32_e32 v17, v225, v17
	v_exp_f32_e32 v229, v229
	s_waitcnt lgkmcnt(3)
	v_mfma_f32_32x32x16_bf16 v[112:127], v[246:249], v[128:131], v[112:127]
	ds_read_b128 v[246:249], v197 offset:33024
	v_add_f32_e32 v17, v226, v17
	v_exp_f32_e32 v230, v230
	s_waitcnt lgkmcnt(3)
	v_mfma_f32_32x32x16_bf16 v[96:111], v[250:253], v[128:131], v[96:111]
	ds_read_b128 v[250:253], v197 offset:45312
	v_add_f32_e32 v17, v227, v17
	v_exp_f32_e32 v231, v231
	s_waitcnt lgkmcnt(3)
	v_mfma_f32_32x32x16_bf16 v[112:127], v[236:239], v[6:9], v[112:127]
	ds_read_b128 v[236:239], v199 offset:33024
	v_cvt_pk_bf16_f32 v28, v224, v225
	v_cvt_pk_bf16_f32 v29, v226, v227
	s_waitcnt lgkmcnt(3)
	v_mfma_f32_32x32x16_bf16 v[96:111], v[240:243], v[6:9], v[96:111]
	ds_read_b128 v[240:243], v199 offset:45312
	ds_read_b128 v[6:9], v195 offset:3072
	v_add_f32_e32 v17, v228, v17
	v_exp_f32_e32 v232, v232
	s_waitcnt lgkmcnt(4)
	v_mfma_f32_32x32x16_bf16 v[112:127], v[246:249], v[10:13], v[112:127]
	ds_read_b128 v[246:249], v198 offset:33024
	v_permlane32_swap_b32_e32 v26, v28
	v_permlane32_swap_b32_e32 v27, v29
	s_waitcnt lgkmcnt(4)
	v_mfma_f32_32x32x16_bf16 v[96:111], v[250:253], v[10:13], v[96:111]
	ds_read_b128 v[250:253], v198 offset:45312
	v_add_f32_e32 v17, v229, v17
	v_exp_f32_e32 v233, v233
	s_waitcnt lgkmcnt(4)
	v_mfma_f32_32x32x16_bf16 v[112:127], v[236:239], v[2:5], v[112:127]
	v_add_f32_e32 v17, v230, v17
	v_exp_f32_e32 v234, v234
	s_waitcnt lgkmcnt(3)
	v_mfma_f32_32x32x16_bf16 v[96:111], v[240:243], v[2:5], v[96:111]
	v_add_f32_e32 v17, v231, v17
	v_exp_f32_e32 v219, v219
	s_waitcnt lgkmcnt(1)
	v_mfma_f32_32x32x16_bf16 v[112:127], v[246:249], v[6:9], v[112:127]
	v_cvt_pk_bf16_f32 v168, v228, v229
	v_cvt_pk_bf16_f32 v169, v230, v231
	s_waitcnt lgkmcnt(0)
	v_mfma_f32_32x32x16_bf16 v[96:111], v[250:253], v[6:9], v[96:111]
	v_add_f32_e32 v17, v232, v17
	v_add_f32_e32 v17, v233, v17
	v_add_f32_e32 v17, v234, v17
	v_add_f32_e32 v17, v219, v17
	v_cvt_pk_bf16_f32 v170, v232, v233
	v_cvt_pk_bf16_f32 v171, v234, v219
	v_mov_b32_e32 v30, v17
	s_nop 1
	v_permlane32_swap_b32_e32 v168, v170
	v_permlane32_swap_b32_e32 v169, v171
	v_permlane32_swap_b32_e32 v17, v30
	s_branch .Lattn_h2_join

.Lattn_h2_join:
	s_add_i32 s7, s7, 2
	s_cmp_le_i32 s7, s6
	s_cselect_b64 s[78:79], -1, 0
	s_cmp_gt_i32 s7, s6
	s_cbranch_scc1 .Lh2_noload
	v_add_co_u32_e32 v6, vcc, 0xfff80000, v178
	s_nop 1
	v_addc_co_u32_e32 v7, vcc, -1, v179, vcc
	global_load_dwordx4 v[2:5], v[6:7], off
	s_nop 0
	global_load_dwordx4 v[6:9], v[6:7], off offset:-256
	s_nop 0
	global_load_dwordx4 v[10:13], v[178:179], off
	global_load_dwordx4 v[160:163], v[178:179], off offset:-256
	global_load_dwordx4 v[164:167], v[176:177], off
.Lh2_noload:
	s_nop 7
	s_nop 3
	s_add_i32 s10, s54, 64
	s_cmp_le_i32 s10, s4
	s_cbranch_scc1 .Lh2_nomask
	v_add_u32_e32 v255, 0x4000003b, v210
	v_cmp_gt_u32_e32 vcc, 2.0, v255
	v_add_u32_e32 v255, 27, v210
	s_nop 0
	v_cndmask_b32_e32 v112, v16, v112, vcc
	v_cmp_lt_u32_e32 vcc, s85, v255
	v_add_u32_e32 v255, 58, v210
	s_nop 0
	v_cndmask_b32_e32 v96, v16, v96, vcc
	v_cmp_lt_u32_e32 vcc, s85, v255
	v_add_u32_e32 v255, 26, v210
	s_nop 0
	v_cndmask_b32_e32 v113, v16, v113, vcc
	v_cmp_lt_u32_e32 vcc, s85, v255
	v_add_u32_e32 v255, 57, v210
	s_nop 0
	v_cndmask_b32_e32 v97, v16, v97, vcc
	v_cmp_lt_u32_e32 vcc, s85, v255
	v_add_u32_e32 v255, 25, v210
	s_nop 0
	v_cndmask_b32_e32 v114, v16, v114, vcc
	v_cmp_lt_u32_e32 vcc, s85, v255
	v_add_u32_e32 v255, 56, v210
	s_nop 0
	v_cndmask_b32_e32 v98, v16, v98, vcc
	v_cmp_lt_u32_e32 vcc, s85, v255
	v_add_u32_e32 v255, 24, v210
	s_nop 0
	v_cndmask_b32_e32 v115, v16, v115, vcc
	v_cmp_lt_u32_e32 vcc, s85, v255
	v_add_u32_e32 v255, 51, v210
	s_nop 0
	v_cndmask_b32_e32 v99, v16, v99, vcc
	v_cmp_lt_u32_e32 vcc, s85, v255
	v_add_u32_e32 v255, 19, v210
	s_nop 0
	v_cndmask_b32_e32 v116, v16, v116, vcc
	v_cmp_lt_u32_e32 vcc, s85, v255
	v_add_u32_e32 v255, 50, v210
	s_nop 0
	v_cndmask_b32_e32 v100, v16, v100, vcc
	v_cmp_lt_u32_e32 vcc, s85, v255
	v_add_u32_e32 v255, 18, v210
	s_nop 0
	v_cndmask_b32_e32 v117, v16, v117, vcc
	v_cmp_lt_u32_e32 vcc, s85, v255
	v_add_u32_e32 v255, 49, v210
	s_nop 0
	v_cndmask_b32_e32 v101, v16, v101, vcc
	v_cmp_lt_u32_e32 vcc, s85, v255
	v_add_u32_e32 v255, 17, v210
	s_nop 0
	v_cndmask_b32_e32 v118, v16, v118, vcc
	v_cmp_lt_u32_e32 vcc, s85, v255
	v_add_u32_e32 v255, 48, v210
	s_nop 0
	v_cndmask_b32_e32 v102, v16, v102, vcc
	v_cmp_lt_u32_e32 vcc, s85, v255
	v_add_u32_e32 v255, 16, v210
	s_nop 0
	v_cndmask_b32_e32 v119, v16, v119, vcc
	v_cmp_lt_u32_e32 vcc, s85, v255
	v_add_u32_e32 v255, 43, v210
	s_nop 0
	v_cndmask_b32_e32 v103, v16, v103, vcc
	v_cmp_lt_u32_e32 vcc, s85, v255
	v_add_u32_e32 v255, 11, v210
	s_nop 0
	v_cndmask_b32_e32 v120, v16, v120, vcc
	v_cmp_lt_u32_e32 vcc, s85, v255
	v_add_u32_e32 v255, 42, v210
	s_nop 0
	v_cndmask_b32_e32 v104, v16, v104, vcc
	v_cmp_lt_u32_e32 vcc, s85, v255
	v_add_u32_e32 v255, 10, v210
	s_nop 0
	v_cndmask_b32_e32 v121, v16, v121, vcc
	v_cmp_lt_u32_e32 vcc, s85, v255
	v_add_u32_e32 v255, 41, v210
	s_nop 0
	v_cndmask_b32_e32 v105, v16, v105, vcc
	v_cmp_lt_u32_e32 vcc, s85, v255
	v_add_u32_e32 v255, 9, v210
	s_nop 0
	v_cndmask_b32_e32 v122, v16, v122, vcc
	v_cmp_lt_u32_e32 vcc, s85, v255
	v_add_u32_e32 v255, 40, v210
	s_nop 0
	v_cndmask_b32_e32 v106, v16, v106, vcc
	v_cmp_lt_u32_e32 vcc, s85, v255
	v_add_u32_e32 v255, 8, v210
	s_nop 0
	v_cndmask_b32_e32 v123, v16, v123, vcc
	v_cmp_lt_u32_e32 vcc, s85, v255
	v_add_u32_e32 v255, 35, v210
	s_nop 0
	v_cndmask_b32_e32 v107, v16, v107, vcc
	v_cmp_lt_u32_e32 vcc, s85, v255
	v_add_u32_e32 v255, 3, v210
	s_nop 0
	v_cndmask_b32_e32 v124, v16, v124, vcc
	v_cmp_lt_u32_e32 vcc, s85, v255
	v_add_u32_e32 v255, 34, v210
	s_nop 0
	v_cndmask_b32_e32 v108, v16, v108, vcc
	v_cmp_lt_u32_e32 vcc, s85, v255
	v_add_u32_e32 v255, 2, v210
	s_nop 0
	v_cndmask_b32_e32 v125, v16, v125, vcc
	v_cmp_lt_u32_e32 vcc, s85, v255
	v_add_u32_e32 v255, 33, v210
	s_nop 0
	v_cndmask_b32_e32 v109, v16, v109, vcc
	v_cmp_lt_u32_e32 vcc, s85, v255
	v_add_u32_e32 v255, 1, v210
	s_nop 0
	v_cndmask_b32_e32 v126, v16, v126, vcc
	v_cmp_lt_u32_e32 vcc, s85, v255
	v_add_u32_e32 v255, 32, v210
	s_nop 0
	v_cndmask_b32_e32 v110, v16, v110, vcc
	v_cmp_lt_u32_e32 vcc, s85, v255
	s_nop 1
	v_cndmask_b32_e32 v127, v16, v127, vcc
	v_cmp_lt_u32_e32 vcc, s85, v210
	s_nop 1
	v_cndmask_b32_e32 v111, v16, v111, vcc
.Lh2_nomask:
	s_andn2_b64 vcc, exec, s[76:77]
	s_cbranch_vccnz .Lh2_nopv
	ds_read_b64_tr_b16 v[236:237], v190 offset:16384
	ds_read_b64_tr_b16 v[238:239], v190 offset:18432
	ds_read_b64_tr_b16 v[240:241], v190 offset:20480
	ds_read_b64_tr_b16 v[242:243], v190 offset:22528
	ds_read_b64_tr_b16 v[246:247], v190 offset:24576
	ds_read_b64_tr_b16 v[248:249], v190 offset:26624
	ds_read_b64_tr_b16 v[250:251], v190 offset:28672
	ds_read_b64_tr_b16 v[252:253], v190 offset:30720
	v_max_f32_e32 v255, v113, v113
	v_max_f32_e32 v245, v112, v112
	v_max_f32_e32 v255, v245, v255
	v_max3_f32 v255, v255, v114, v115
	v_max3_f32 v255, v255, v116, v117
	v_max3_f32 v255, v255, v118, v119
	v_max3_f32 v255, v255, v120, v121
	v_max3_f32 v255, v255, v122, v123
	v_max3_f32 v255, v255, v124, v125
	v_max3_f32 v255, v255, v126, v127
	v_max3_f32 v255, v255, v96, v97
	v_max3_f32 v255, v255, v98, v99
	v_max3_f32 v255, v255, v100, v101
	v_max3_f32 v255, v255, v102, v103
	v_max3_f32 v255, v255, v104, v105
	v_max3_f32 v255, v255, v106, v107
	v_max3_f32 v255, v255, v108, v109
	v_max3_f32 v255, v255, v110, v111
	s_waitcnt lgkmcnt(6)
	v_mfma_f32_32x32x16_bf16 v[80:95], v[18:21], v[236:239], v[80:95]
	ds_read_b64_tr_b16 v[236:237], v190 offset:16896
	ds_read_b64_tr_b16 v[238:239], v190 offset:18944
	v_mov_b32_e32 v245, v255
	s_nop 1
	v_permlane32_swap_b32_e32 v255, v245
	v_max_f32_e32 v245, v245, v245
	s_waitcnt lgkmcnt(6)
	v_mfma_f32_32x32x16_bf16 v[80:95], v[22:25], v[240:243], v[80:95]
	ds_read_b64_tr_b16 v[240:241], v190 offset:20992
	ds_read_b64_tr_b16 v[242:243], v190 offset:23040
	v_max_f32_e32 v255, v255, v255
	v_max_f32_e32 v255, v255, v245
	v_sub_f32_e32 v245, v255, v180
	v_mul_f32_e32 v245, 0x3d93cd3a, v245
	s_waitcnt lgkmcnt(6)
	v_mfma_f32_32x32x16_bf16 v[80:95], v[26:29], v[246:249], v[80:95]
	ds_read_b64_tr_b16 v[246:247], v190 offset:25088
	ds_read_b64_tr_b16 v[248:249], v190 offset:27136
	v_cmp_ge_f32_e32 vcc, s86, v245
	s_cmp_eq_u64 vcc, exec
	s_cselect_b64 s[10:11], -1, 0
	v_max_f32_e32 v235, v180, v180
	s_waitcnt lgkmcnt(6)
	v_mfma_f32_32x32x16_bf16 v[80:95], v[168:171], v[250:253], v[80:95]
	ds_read_b64_tr_b16 v[250:251], v190 offset:29184
	ds_read_b64_tr_b16 v[252:253], v190 offset:31232
	v_max_f32_e32 v245, v235, v255
	v_sub_f32_e32 v235, v180, v245
	v_mul_f32_e32 v235, 0x3dd53b94, v235
	v_exp_f32_e32 v235, v235
	s_waitcnt lgkmcnt(6)
	v_mfma_f32_32x32x16_bf16 v[64:79], v[18:21], v[236:239], v[64:79]
	ds_read_b64_tr_b16 v[236:237], v190 offset:17408
	ds_read_b64_tr_b16 v[238:239], v190 offset:19456
	v_cndmask_b32_e64 v208, v245, v180, s[10:11]
	v_cndmask_b32_e64 v235, v235, 1.0, s[10:11]
	v_mul_f32_e32 v254, 0xbdd53b94, v208
	v_mov_b32_e32 v213, v254
	s_waitcnt lgkmcnt(6)
	v_mfma_f32_32x32x16_bf16 v[64:79], v[22:25], v[240:243], v[64:79]
	ds_read_b64_tr_b16 v[240:241], v190 offset:21504
	ds_read_b64_tr_b16 v[242:243], v190 offset:23552
	v_fmamk_f32 v224, v112, 0x3dd53b94, v254
	v_fmamk_f32 v226, v113, 0x3dd53b94, v254
	v_fmamk_f32 v222, v114, 0x3dd53b94, v254
	v_fmamk_f32 v225, v115, 0x3dd53b94, v254
	s_waitcnt lgkmcnt(6)
	v_mfma_f32_32x32x16_bf16 v[64:79], v[26:29], v[246:249], v[64:79]
	ds_read_b64_tr_b16 v[246:247], v190 offset:25600
	ds_read_b64_tr_b16 v[248:249], v190 offset:27648
	v_fmamk_f32 v220, v116, 0x3dd53b94, v254
	v_fmamk_f32 v223, v117, 0x3dd53b94, v254
	v_fmamk_f32 v219, v118, 0x3dd53b94, v254
	s_waitcnt lgkmcnt(6)
	v_mfma_f32_32x32x16_bf16 v[64:79], v[168:171], v[250:253], v[64:79]
	ds_read_b64_tr_b16 v[250:251], v190 offset:29696
	ds_read_b64_tr_b16 v[252:253], v190 offset:31744
	v_fmamk_f32 v221, v119, 0x3dd53b94, v254
	v_fmamk_f32 v216, v120, 0x3dd53b94, v254
	v_fmamk_f32 v218, v121, 0x3dd53b94, v254
	s_waitcnt lgkmcnt(6)
	v_mfma_f32_32x32x16_bf16 v[48:63], v[18:21], v[236:239], v[48:63]
	ds_read_b64_tr_b16 v[236:237], v190 offset:17920
	ds_read_b64_tr_b16 v[238:239], v190 offset:19968
	v_fmamk_f32 v214, v122, 0x3dd53b94, v254
	v_fmamk_f32 v217, v123, 0x3dd53b94, v254
	v_fmamk_f32 v212, v124, 0x3dd53b94, v254
	s_waitcnt lgkmcnt(6)
	v_mfma_f32_32x32x16_bf16 v[48:63], v[22:25], v[240:243], v[48:63]
	ds_read_b64_tr_b16 v[240:241], v190 offset:22016
	ds_read_b64_tr_b16 v[242:243], v190 offset:24064
	v_fmamk_f32 v215, v125, 0x3dd53b94, v254
	v_fmamk_f32 v211, v126, 0x3dd53b94, v254
	v_fmac_f32_e32 v213, 0x3dd53b94, v127
	s_waitcnt lgkmcnt(6)
	v_mfma_f32_32x32x16_bf16 v[48:63], v[26:29], v[246:249], v[48:63]
	ds_read_b64_tr_b16 v[246:247], v190 offset:26112
	ds_read_b64_tr_b16 v[248:249], v190 offset:28160
	v_exp_f32_e32 v224, v224
	v_exp_f32_e32 v226, v226
	v_exp_f32_e32 v222, v222
	s_waitcnt lgkmcnt(6)
	v_mfma_f32_32x32x16_bf16 v[48:63], v[168:171], v[250:253], v[48:63]
	ds_read_b64_tr_b16 v[250:251], v190 offset:30208
	ds_read_b64_tr_b16 v[252:253], v190 offset:32256
	v_exp_f32_e32 v225, v225
	v_exp_f32_e32 v220, v220
	v_exp_f32_e32 v223, v223
	s_waitcnt lgkmcnt(6)
	v_mfma_f32_32x32x16_bf16 v[32:47], v[18:21], v[236:239], v[32:47]
	v_exp_f32_e32 v219, v219
	v_exp_f32_e32 v221, v221
	v_exp_f32_e32 v216, v216
	s_waitcnt lgkmcnt(4)
	v_mfma_f32_32x32x16_bf16 v[32:47], v[22:25], v[240:243], v[32:47]
	v_exp_f32_e32 v218, v218
	v_exp_f32_e32 v214, v214
	v_exp_f32_e32 v217, v217
	s_waitcnt lgkmcnt(2)
	v_mfma_f32_32x32x16_bf16 v[32:47], v[26:29], v[246:249], v[32:47]
	v_exp_f32_e32 v212, v212
	v_exp_f32_e32 v215, v215
	v_exp_f32_e32 v211, v211
	s_waitcnt lgkmcnt(0)
	v_mfma_f32_32x32x16_bf16 v[32:47], v[168:171], v[250:253], v[32:47]
	v_exp_f32_e32 v213, v213
	v_pk_fma_f32 v[182:183], v[96:97], s[30:31], v[254:255] op_sel_hi:[1,0,0]
	v_pk_fma_f32 v[180:181], v[98:99], s[30:31], v[254:255] op_sel_hi:[1,0,0]
	s_branch .Lh2_post
.Lh2_nopv:
	v_max_f32_e32 v255, v113, v113
	v_max_f32_e32 v245, v112, v112
	v_max_f32_e32 v255, v245, v255
	v_max3_f32 v255, v255, v114, v115
	v_max3_f32 v255, v255, v116, v117
	v_max3_f32 v255, v255, v118, v119
	v_max3_f32 v255, v255, v120, v121
	v_max3_f32 v255, v255, v122, v123
	v_max3_f32 v255, v255, v124, v125
	v_max3_f32 v255, v255, v126, v127
	v_max3_f32 v255, v255, v96, v97
	v_max3_f32 v255, v255, v98, v99
	v_max3_f32 v255, v255, v100, v101
	v_max3_f32 v255, v255, v102, v103
	v_max3_f32 v255, v255, v104, v105
	v_max3_f32 v255, v255, v106, v107
	v_max3_f32 v255, v255, v108, v109
	v_max3_f32 v255, v255, v110, v111
	v_mov_b32_e32 v245, v255
	s_nop 1
	v_permlane32_swap_b32_e32 v255, v245
	v_max_f32_e32 v245, v245, v245
	v_max_f32_e32 v255, v255, v255
	v_max_f32_e32 v255, v255, v245
	v_sub_f32_e32 v245, v255, v180
	v_mul_f32_e32 v245, 0x3d93cd3a, v245
	v_cmp_ge_f32_e32 vcc, s86, v245
	s_cmp_eq_u64 vcc, exec
	s_cselect_b64 s[10:11], -1, 0
	v_max_f32_e32 v235, v180, v180
	v_max_f32_e32 v245, v235, v255
	v_sub_f32_e32 v235, v180, v245
	v_mul_f32_e32 v235, 0x3dd53b94, v235
	v_exp_f32_e32 v235, v235
	v_cndmask_b32_e64 v208, v245, v180, s[10:11]
	v_cndmask_b32_e64 v235, v235, 1.0, s[10:11]
	v_mul_f32_e32 v254, 0xbdd53b94, v208
	v_mov_b32_e32 v213, v254
	v_fmamk_f32 v224, v112, 0x3dd53b94, v254
	v_fmamk_f32 v226, v113, 0x3dd53b94, v254
	v_fmamk_f32 v222, v114, 0x3dd53b94, v254
	v_fmamk_f32 v225, v115, 0x3dd53b94, v254
	v_fmamk_f32 v220, v116, 0x3dd53b94, v254
	v_fmamk_f32 v223, v117, 0x3dd53b94, v254
	v_fmamk_f32 v219, v118, 0x3dd53b94, v254
	v_fmamk_f32 v221, v119, 0x3dd53b94, v254
	v_fmamk_f32 v216, v120, 0x3dd53b94, v254
	v_fmamk_f32 v218, v121, 0x3dd53b94, v254
	v_fmamk_f32 v214, v122, 0x3dd53b94, v254
	v_fmamk_f32 v217, v123, 0x3dd53b94, v254
	v_fmamk_f32 v212, v124, 0x3dd53b94, v254
	v_fmamk_f32 v215, v125, 0x3dd53b94, v254
	v_fmamk_f32 v211, v126, 0x3dd53b94, v254
	v_fmac_f32_e32 v213, 0x3dd53b94, v127
	v_exp_f32_e32 v224, v224
	v_exp_f32_e32 v226, v226
	v_exp_f32_e32 v222, v222
	v_exp_f32_e32 v225, v225
	v_exp_f32_e32 v220, v220
	v_exp_f32_e32 v223, v223
	v_exp_f32_e32 v219, v219
	v_exp_f32_e32 v221, v221
	v_exp_f32_e32 v216, v216
	v_exp_f32_e32 v218, v218
	v_exp_f32_e32 v214, v214
	v_exp_f32_e32 v217, v217
	v_exp_f32_e32 v212, v212
	v_exp_f32_e32 v215, v215
	v_exp_f32_e32 v211, v211
	v_exp_f32_e32 v213, v213
	v_pk_fma_f32 v[182:183], v[96:97], s[30:31], v[254:255] op_sel_hi:[1,0,0]
	v_pk_fma_f32 v[180:181], v[98:99], s[30:31], v[254:255] op_sel_hi:[1,0,0]
.Lh2_post:
	s_andn2_b64 vcc, exec, s[78:79]
	s_cbranch_vccnz .Lh2_nokw
	s_waitcnt vmcnt(0)
	ds_write_b128 v209, v[6:9]
	ds_write_b128 v209, v[160:163] offset:12288
	ds_write_b128 v203, v[164:167] offset:57344
.Lh2_nokw:
	v_cmp_gt_f32_e32 vcc, 1.0, v235
	s_cbranch_vccz .Lh2_norsc
	s_and_saveexec_b64 s[76:77], s[8:9]
	s_cbranch_execz .Lh2_rsc2
	ds_write_b32 v192, v235 offset:128
.Lh2_rsc2:
	s_or_b64 exec, exec, s[76:77]
	s_waitcnt lgkmcnt(0)
	ds_read_b128 v[18:21], v189 offset:224
	ds_read_b128 v[22:25], v189 offset:192
	ds_read_b128 v[26:29], v189 offset:160
	ds_read_b128 v[168:171], v189 offset:128
	s_waitcnt lgkmcnt(3)
	v_pk_mul_f32 v[94:95], v[94:95], v[20:21]
	s_waitcnt lgkmcnt(2)
	v_pk_mul_f32 v[90:91], v[90:91], v[24:25]
	s_waitcnt lgkmcnt(1)
	v_pk_mul_f32 v[86:87], v[86:87], v[28:29]
	s_waitcnt lgkmcnt(0)
	v_pk_mul_f32 v[82:83], v[82:83], v[170:171]
	v_pk_mul_f32 v[92:93], v[92:93], v[18:19]
	v_pk_mul_f32 v[88:89], v[88:89], v[22:23]
	v_pk_mul_f32 v[84:85], v[84:85], v[26:27]
	v_pk_mul_f32 v[80:81], v[80:81], v[168:169]
	v_pk_mul_f32 v[78:79], v[78:79], v[20:21]
	v_pk_mul_f32 v[74:75], v[74:75], v[24:25]
	v_pk_mul_f32 v[70:71], v[70:71], v[28:29]
	v_pk_mul_f32 v[66:67], v[66:67], v[170:171]
	v_pk_mul_f32 v[76:77], v[76:77], v[18:19]
	v_pk_mul_f32 v[72:73], v[72:73], v[22:23]
	v_pk_mul_f32 v[68:69], v[68:69], v[26:27]
	v_pk_mul_f32 v[64:65], v[64:65], v[168:169]
	v_pk_mul_f32 v[62:63], v[62:63], v[20:21]
	v_pk_mul_f32 v[58:59], v[58:59], v[24:25]
	v_pk_mul_f32 v[54:55], v[54:55], v[28:29]
	v_pk_mul_f32 v[50:51], v[50:51], v[170:171]
	v_pk_mul_f32 v[60:61], v[60:61], v[18:19]
	v_pk_mul_f32 v[56:57], v[56:57], v[22:23]
	v_pk_mul_f32 v[52:53], v[52:53], v[26:27]
	v_pk_mul_f32 v[48:49], v[48:49], v[168:169]
	v_pk_mul_f32 v[46:47], v[46:47], v[20:21]
	v_pk_mul_f32 v[42:43], v[42:43], v[24:25]
	v_pk_mul_f32 v[38:39], v[38:39], v[28:29]
	v_pk_mul_f32 v[34:35], v[34:35], v[170:171]
	v_pk_mul_f32 v[44:45], v[44:45], v[18:19]
	v_pk_mul_f32 v[40:41], v[40:41], v[22:23]
	v_pk_mul_f32 v[36:37], v[36:37], v[26:27]
	v_pk_mul_f32 v[32:33], v[32:33], v[168:169]
.Lh2_norsc:
	v_pk_fma_f32 v[160:161], v[110:111], s[30:31], v[254:255] op_sel_hi:[1,0,0]
	v_pk_fma_f32 v[162:163], v[108:109], s[30:31], v[254:255] op_sel_hi:[1,0,0]
	v_pk_fma_f32 v[164:165], v[106:107], s[30:31], v[254:255] op_sel_hi:[1,0,0]
	v_pk_fma_f32 v[166:167], v[104:105], s[30:31], v[254:255] op_sel_hi:[1,0,0]
	v_pk_fma_f32 v[168:169], v[102:103], s[30:31], v[254:255] op_sel_hi:[1,0,0]
	v_pk_fma_f32 v[170:171], v[100:101], s[30:31], v[254:255] op_sel_hi:[1,0,0]
	v_add_f32_e32 v0, v0, v14
	s_mov_b64 s[10:11], 0x4000
	v_fmac_f32_e32 v0, v191, v194
	v_add_f32_e32 v194, v17, v30
	v_lshl_add_u64 v[176:177], v[176:177], 0, s[10:11]
	s_mov_b64 s[10:11], 0x200000
	s_addk_i32 s54, 0x80
	v_fmac_f32_e32 v194, v0, v15
	v_lshl_add_u64 v[178:179], v[178:179], 0, s[10:11]
	v_add_u32_e32 v210, 0xffffff80, v210
	v_mov_b32_e32 v191, v235
	s_waitcnt lgkmcnt(0)
	s_barrier
	s_andn2_b64 vcc, exec, s[78:79]
	s_cbranch_vccnz .Lh2_nov
	ds_write_b128 v200, v[2:5] offset:16384
	ds_write_b128 v201, v[10:13] offset:16384
.Lh2_nov:
	s_cmp_ge_i32 s7, s6
	s_cbranch_scc1 .LBB0_420
	s_branch .LBB0_394
